# all four attention mixers: K/bias/F/V fragment reads of a key tile issued together with counted waits, MFMAs back-to-back; lazy softmax rescale; VAR0 max tree via v_max3
# baseline (speedup 1.0000x reference)
; #define LAS __attribute__((address_space(3)))
; template <bool MASK>
; __device__ __forceinline__ void sb_weights(f32x16& p0, f32x16& p1, float tlf, int hi, float& R) {
;     float Tm[8];
; #pragma unroll
;     for (int hf = 0; hf < 2; ++hf)
; #pragma unroll
;         for (int a = 0; a < 4; ++a) {
;             float om[4], be[4];
; #pragma unroll
;             for (int j = 0; j < 4; ++j) {
;                 const float z = hf ? p1[4 * a + j] : p0[4 * a + j];
;                 const float o_ = __builtin_amdgcn_rcpf(1.0f + __builtin_amdgcn_exp2f(z));
;                 if (MASK) { const float vf_ = __builtin_amdgcn_fmed3f(tlf - (float)(32 * hf + 8 * a + j), 0.f, 1.f), dl = o_ - 1.0f; om[j] = __builtin_fmaf(vf_, dl, 1.0f); be[j] = -vf_ * dl; }
;                 else { om[j] = o_; be[j] = 1.0f - o_; }
;             }
; template <int VAR>
; __device__ __forceinline__ void attn_unit(LAS unsigned char* lds, const AttnArgs& A, int b, int h, int qb, const int tid) {
;     ...
;                 f32x16 p0, p1;
; #pragma unroll
;                 for (int r = 0; r < 16; ++r) { p0[r] = 0.f; p1[r] = 0.f; }
;                 __builtin_amdgcn_s_setprio(1);
; #pragma unroll
;                 for (int d0 = 0; d0 < 4; ++d0) {
;                     const bf16x8 b0 = *(const LAS bf16x8*)(kb + d0 * 2048), b1 = *(const LAS bf16x8*)(kb + d0 * 2048 + 512);
;                     p0 = __builtin_amdgcn_mfma_f32_32x32x16_bf16(b0, qr[d0], p0, 0, 0, 0);
;                     p1 = __builtin_amdgcn_mfma_f32_32x32x16_bf16(b1, qr[d0], p1, 0, 0, 0);
;                 }
;                 __builtin_amdgcn_s_setprio(0);
.LBB0_435:
	s_add_i32 s38, s85, 2
	s_and_b32 s70, s83, 1
	s_cmp_gt_i32 s38, s13
	s_cselect_b64 s[38:39], -1, 0
	s_or_b64 s[38:39], s[38:39], s[68:69]
	s_and_b64 vcc, exec, s[38:39]
	s_cbranch_vccnz .LBB0_443
	s_lshl_b32 s50, s70, 13
	v_add_u32_e32 v0, s50, v125
	s_cmp_lg_u32 s84, s83
	s_setprio 1
	ds_read_b128 v[224:227], v0
	ds_read_b128 v[228:231], v0 offset:512
	ds_read_b128 v[232:235], v0 offset:2048
	ds_read_b128 v[236:239], v0 offset:2560
	ds_read_b128 v[240:243], v0 offset:4096
	ds_read_b128 v[244:247], v0 offset:4608
	ds_read_b128 v[248:251], v0 offset:6144
	ds_read_b128 v[2:5], v0 offset:6656
	v_add_u32_e32 v194, s50, v177
	s_waitcnt vmcnt(5) lgkmcnt(7)
	v_mfma_f32_32x32x16_bf16 v[64:79], v[224:227], v[80:83], 0
	s_waitcnt lgkmcnt(6)
	v_mfma_f32_32x32x16_bf16 v[48:63], v[228:231], v[80:83], 0
	s_waitcnt vmcnt(4) lgkmcnt(5)
	v_mfma_f32_32x32x16_bf16 v[64:79], v[232:235], v[84:87], v[64:79]
	s_waitcnt lgkmcnt(4)
	v_mfma_f32_32x32x16_bf16 v[48:63], v[236:239], v[84:87], v[48:63]
	s_waitcnt vmcnt(3) lgkmcnt(3)
	v_mfma_f32_32x32x16_bf16 v[64:79], v[240:243], v[88:91], v[64:79]
	s_waitcnt lgkmcnt(2)
	v_mfma_f32_32x32x16_bf16 v[48:63], v[244:247], v[88:91], v[48:63]
	s_waitcnt vmcnt(2) lgkmcnt(1)
	v_mfma_f32_32x32x16_bf16 v[64:79], v[248:251], v[92:95], v[64:79]
	s_waitcnt lgkmcnt(0)
	v_mfma_f32_32x32x16_bf16 v[48:63], v[2:5], v[92:95], v[48:63]
	ds_read_b64_tr_b16 v[224:225], v194 offset:16384
	ds_read_b64_tr_b16 v[226:227], v194 offset:16896
	ds_read_b64_tr_b16 v[228:229], v194 offset:17408
	ds_read_b64_tr_b16 v[230:231], v194 offset:17920
	ds_read_b64_tr_b16 v[232:233], v194 offset:18432
	ds_read_b64_tr_b16 v[234:235], v194 offset:18944
	ds_read_b64_tr_b16 v[236:237], v194 offset:19456
	ds_read_b64_tr_b16 v[238:239], v194 offset:19968
	ds_read_b64_tr_b16 v[240:241], v194 offset:20480
	ds_read_b64_tr_b16 v[242:243], v194 offset:20992
	ds_read_b64_tr_b16 v[244:245], v194 offset:21504
	ds_read_b64_tr_b16 v[246:247], v194 offset:22016
	ds_read_b64_tr_b16 v[248:249], v194 offset:22528
	ds_read_b64_tr_b16 v[250:251], v194 offset:23040
	s_setprio 0
	s_nop 7
	v_exp_f32_e32 v0, v64
	v_exp_f32_e32 v221, v65
	v_exp_f32_e32 v219, v66
	v_exp_f32_e32 v218, v67
	v_add_f32_e32 v0, 1.0, v0
	v_rcp_f32_e32 v64, v0
	v_exp_f32_e32 v220, v68
	v_exp_f32_e32 v217, v69
	v_exp_f32_e32 v216, v70
	v_exp_f32_e32 v215, v71
	v_exp_f32_e32 v214, v72
	v_exp_f32_e32 v213, v73
	v_exp_f32_e32 v212, v74
	v_exp_f32_e32 v210, v75
	v_exp_f32_e32 v211, v76
	v_exp_f32_e32 v209, v77
	v_exp_f32_e32 v208, v78
	v_exp_f32_e32 v207, v79
	v_exp_f32_e32 v206, v48
	v_exp_f32_e32 v205, v49
	v_exp_f32_e32 v193, v50
	v_exp_f32_e32 v191, v51
	v_exp_f32_e32 v192, v52
	v_exp_f32_e32 v190, v53
	v_exp_f32_e32 v189, v54
	v_exp_f32_e32 v188, v55
	v_exp_f32_e32 v187, v56
	v_exp_f32_e32 v186, v57
	v_exp_f32_e32 v185, v58
	v_exp_f32_e32 v183, v59
	v_exp_f32_e32 v184, v60
	v_exp_f32_e32 v182, v61
	v_exp_f32_e32 v181, v62
	v_exp_f32_e32 v180, v63
	s_mov_b64 s[68:69], -1
	s_cbranch_scc0 .LBB0_438
; template <bool MASK>
; __device__ __forceinline__ void sb_weights(f32x16& p0, f32x16& p1, float tlf, int hi, float& R) {
;     ...
;         for (int a = 0; a < 4; ++a) {
;             float om[4], be[4];
; #pragma unroll
;             for (int j = 0; j < 4; ++j) {
;                 const float z = hf ? p1[4 * a + j] : p0[4 * a + j];
;                 const float o_ = __builtin_amdgcn_rcpf(1.0f + __builtin_amdgcn_exp2f(z));
;                 if (MASK) { const float vf_ = __builtin_amdgcn_fmed3f(tlf - (float)(32 * hf + 8 * a + j), 0.f, 1.f), dl = o_ - 1.0f; om[j] = __builtin_fmaf(vf_, dl, 1.0f); be[j] = -vf_ * dl; }
;                 else { om[j] = o_; be[j] = 1.0f - o_; }
;             }
;             const float s2 = om[3], s1 = om[3] * om[2], s0 = s1 * om[1];
;             Tm[4 * hf + a] = s0 * om[0];
;             if (hf) { p1[4 * a + 3] = be[3]; p1[4 * a + 2] = be[2] * s2; p1[4 * a + 1] = be[1] * s1; p1[4 * a] = be[0] * s0; }
;             else    { p0[4 * a + 3] = be[3]; p0[4 * a + 2] = be[2] * s2; p0[4 * a + 1] = be[1] * s1; p0[4 * a] = be[0] * s0; }
;         }
;     float U[8], Th[8], PS[8];
; #pragma unroll
;     for (int k = 0; k < 8; ++k) { float lo_; lohi(Tm[k], lo_, Th[k]); U[k] = lo_ * Th[k]; }
	v_add_f32_e32 v7, 1.0, v217
	v_add_f32_e32 v0, 1.0, v221
	v_rcp_f32_e32 v10, v7
	v_add_f32_e32 v7, 1.0, v216
	v_rcp_f32_e32 v65, v0
	v_add_f32_e32 v0, 1.0, v219
	v_rcp_f32_e32 v11, v7
	v_add_f32_e32 v7, 1.0, v215
	v_rcp_f32_e32 v4, v0
	v_add_f32_e32 v0, 1.0, v218
	v_rcp_f32_e32 v7, v7
	v_rcp_f32_e32 v6, v0
	v_add_f32_e32 v5, 1.0, v220
	v_rcp_f32_e32 v5, v5
	v_mul_f32_e32 v14, v7, v11
	v_mul_f32_e32 v9, v6, v4
	v_mul_f32_e32 v49, v10, v14
	v_pk_add_f32 v[2:3], v[64:65], 1.0 op_sel_hi:[1,0] neg_lo:[1,0] neg_hi:[1,0]
	v_mul_f32_e32 v8, v65, v9
	v_pk_add_f32 v[12:13], v[4:5], 1.0 op_sel_hi:[1,0] neg_lo:[1,0] neg_hi:[1,0]
	v_mul_f32_e32 v68, v5, v49
	v_pk_add_f32 v[4:5], v[6:7], 1.0 op_sel_hi:[1,0] neg_lo:[1,0] neg_hi:[1,0]
	v_mov_b32_e32 v15, v7
	v_add_f32_e32 v7, 1.0, v214
	v_mul_f32_e32 v0, v64, v8
	v_pk_mul_f32 v[2:3], v[2:3], v[8:9]
	v_pk_add_f32 v[8:9], v[10:11], 1.0 op_sel_hi:[1,0] neg_lo:[1,0] neg_hi:[1,0]
	v_rcp_f32_e32 v10, v7
	v_add_f32_e32 v7, 1.0, v213
	v_rcp_f32_e32 v11, v7
	v_add_f32_e32 v7, 1.0, v212
	v_pk_mul_f32 v[8:9], v[14:15], v[8:9]
	v_rcp_f32_e32 v14, v7
	v_add_f32_e32 v7, 1.0, v210
	v_rcp_f32_e32 v48, v7
	v_mov_b32_e32 v7, v49
	v_pk_mul_f32 v[6:7], v[6:7], v[12:13]
	v_pk_add_f32 v[12:13], v[10:11], 1.0 op_sel_hi:[1,0] neg_lo:[1,0] neg_hi:[1,0]
	v_mul_f32_e32 v51, v48, v14
	v_mul_f32_e32 v50, v11, v51
	v_mul_f32_e32 v69, v10, v50
	v_add_f32_e32 v10, 1.0, v211
	v_rcp_f32_e32 v15, v10
	v_add_f32_e32 v10, 1.0, v209
	v_rcp_f32_e32 v52, v10
	v_add_f32_e32 v10, 1.0, v208
	v_rcp_f32_e32 v53, v10
	v_add_f32_e32 v10, 1.0, v207
	v_rcp_f32_e32 v49, v10
	v_pk_mul_f32 v[10:11], v[12:13], v[50:51]
	v_pk_add_f32 v[50:51], v[14:15], 1.0 op_sel_hi:[1,0] neg_lo:[1,0] neg_hi:[1,0]
	v_pk_add_f32 v[12:13], v[52:53], 1.0 op_sel_hi:[1,0] neg_lo:[1,0] neg_hi:[1,0]
	v_mul_f32_e32 v54, v49, v53
	v_mul_f32_e32 v57, v52, v54
	v_mul_f32_e32 v75, v15, v57
	v_pk_add_f32 v[14:15], v[48:49], 1.0 op_sel_hi:[1,0] neg_lo:[1,0] neg_hi:[1,0]
	v_mov_b32_e32 v55, v49
	v_add_f32_e32 v49, 1.0, v206
	v_rcp_f32_e32 v52, v49
	v_add_f32_e32 v49, 1.0, v205
	v_rcp_f32_e32 v53, v49
	v_add_f32_e32 v49, 1.0, v193
	v_pk_mul_f32 v[12:13], v[54:55], v[12:13]
	v_rcp_f32_e32 v54, v49
	v_add_f32_e32 v49, 1.0, v191
	v_rcp_f32_e32 v56, v49
	v_mov_b32_e32 v49, v57
	v_pk_mul_f32 v[48:49], v[48:49], v[50:51]
	v_pk_add_f32 v[50:51], v[52:53], 1.0 op_sel_hi:[1,0] neg_lo:[1,0] neg_hi:[1,0]
	v_mul_f32_e32 v59, v56, v54
	v_mul_f32_e32 v58, v53, v59
	v_mul_f32_e32 v74, v52, v58
	v_add_f32_e32 v52, 1.0, v192
	v_add_f32_e32 v53, 1.0, v189
	v_add_f32_e32 v57, 1.0, v188
	v_rcp_f32_e32 v55, v52
	v_add_f32_e32 v52, 1.0, v190
	v_rcp_f32_e32 v53, v53
	v_rcp_f32_e32 v57, v57
	v_rcp_f32_e32 v52, v52
	v_pk_mul_f32 v[50:51], v[50:51], v[58:59]
	v_pk_add_f32 v[58:59], v[54:55], 1.0 op_sel_hi:[1,0] neg_lo:[1,0] neg_hi:[1,0]
	v_mul_f32_e32 v62, v57, v53
	v_mul_f32_e32 v65, v52, v62
	v_pk_add_f32 v[60:61], v[52:53], 1.0 op_sel_hi:[1,0] neg_lo:[1,0] neg_hi:[1,0]
	v_mul_f32_e32 v79, v55, v65
	v_pk_add_f32 v[54:55], v[56:57], 1.0 op_sel_hi:[1,0] neg_lo:[1,0] neg_hi:[1,0]
	v_mov_b32_e32 v63, v57
	v_add_f32_e32 v57, 1.0, v187
	v_pk_mul_f32 v[52:53], v[62:63], v[60:61]
	v_rcp_f32_e32 v60, v57
	v_add_f32_e32 v57, 1.0, v186
	v_rcp_f32_e32 v61, v57
	v_add_f32_e32 v57, 1.0, v185
	v_rcp_f32_e32 v62, v57
	v_add_f32_e32 v57, 1.0, v183
	v_rcp_f32_e32 v66, v57
	v_mov_b32_e32 v57, v65
	v_pk_mul_f32 v[56:57], v[56:57], v[58:59]
	v_pk_add_f32 v[58:59], v[60:61], 1.0 op_sel_hi:[1,0] neg_lo:[1,0] neg_hi:[1,0]
	v_mul_f32_e32 v71, v66, v62
	v_mul_f32_e32 v70, v61, v71
	v_mul_f32_e32 v78, v60, v70
	v_add_f32_e32 v60, 1.0, v184
	v_rcp_f32_e32 v63, v60
	v_add_f32_e32 v60, 1.0, v182
	v_add_f32_e32 v61, 1.0, v181
	v_add_f32_e32 v65, 1.0, v180
	v_rcp_f32_e32 v60, v60
	v_rcp_f32_e32 v61, v61
	v_rcp_f32_e32 v67, v65
	v_pk_mul_f32 v[58:59], v[58:59], v[70:71]
	v_pk_add_f32 v[70:71], v[62:63], 1.0 op_sel_hi:[1,0] neg_lo:[1,0] neg_hi:[1,0]
	v_pk_add_f32 v[72:73], v[60:61], 1.0 op_sel_hi:[1,0] neg_lo:[1,0] neg_hi:[1,0]
	v_mul_f32_e32 v76, v67, v61
	v_mov_b32_e32 v77, v67
	v_mul_f32_e32 v65, v60, v76
	v_pk_mul_f32 v[60:61], v[76:77], v[72:73]
	v_mov_b32_e32 v73, v75
	v_mov_b32_e32 v72, v74
	v_mul_f32_e32 v222, v63, v65
	v_pk_add_f32 v[62:63], v[66:67], 1.0 op_sel_hi:[1,0] neg_lo:[1,0] neg_hi:[1,0]
	v_mov_b32_e32 v67, v65
	v_permlane32_swap_b32_e32 v75, v73
	v_permlane32_swap_b32_e32 v74, v72
	v_pk_mul_f32 v[66:67], v[66:67], v[70:71]
	v_mov_b32_e32 v70, v68
	v_mov_b32_e32 v71, v69
	v_pk_mul_f32 v[76:77], v[74:75], v[72:73]
	v_mov_b32_e32 v75, v79
	v_mov_b32_e32 v74, v78
	v_mov_b32_e32 v65, v0
	v_permlane32_swap_b32_e32 v68, v70
	v_permlane32_swap_b32_e32 v69, v71
	v_permlane32_swap_b32_e32 v79, v75
	v_permlane32_swap_b32_e32 v78, v74
	v_mov_b32_e32 v223, v222
	v_permlane32_swap_b32_e32 v0, v65
	v_pk_mul_f32 v[68:69], v[68:69], v[70:71]
	v_pk_mul_f32 v[78:79], v[78:79], v[74:75]
	v_permlane32_swap_b32_e32 v222, v223
	s_mov_b64 s[68:69], 0

; #define LAS __attribute__((address_space(3)))
; __device__ __forceinline__ unsigned cvtpk(float lo, float hi) { f32x2_t v = {lo, hi}; bf16x2_t b = __builtin_convertvector(v, bf16x2_t); return __builtin_bit_cast(unsigned, b); }
; __device__ __forceinline__ s16x4 vtr(const LAS unsigned char* p) { return __builtin_bit_cast(s16x4, __builtin_amdgcn_ds_read_tr16_b64_v4i16((LAS v4i16_t*)p)); }
; __device__ __forceinline__ void pv(f32x16 (&o)[2], const LAS unsigned char* vp, const f32x16& p0, const f32x16& p1) {
;     u32x4 pw[4];
;     pw[0] = (u32x4){cvtpk(p0[0], p0[1]), cvtpk(p0[2], p0[3]), cvtpk(p0[4], p0[5]), cvtpk(p0[6], p0[7])};
;     pw[1] = (u32x4){cvtpk(p0[8], p0[9]), cvtpk(p0[10], p0[11]), cvtpk(p0[12], p0[13]), cvtpk(p0[14], p0[15])};
;     pw[2] = (u32x4){cvtpk(p1[0], p1[1]), cvtpk(p1[2], p1[3]), cvtpk(p1[4], p1[5]), cvtpk(p1[6], p1[7])};
;     pw[3] = (u32x4){cvtpk(p1[8], p1[9]), cvtpk(p1[10], p1[11]), cvtpk(p1[12], p1[13]), cvtpk(p1[14], p1[15])};
;     __builtin_amdgcn_s_setprio(1);
; #pragma unroll
;     for (int dh = 0; dh < 2; ++dh)
; #pragma unroll
;         for (int ks = 0; ks < 4; ++ks) {
;             const s16x4 lo = vtr(vp + dh * 4096 + ks * 1024), hi_ = vtr(vp + dh * 4096 + ks * 1024 + 512);
;             const bf16x8 vf = __builtin_shufflevector(lo, hi_, 0, 1, 2, 3, 4, 5, 6, 7);
;             o[dh] = __builtin_amdgcn_mfma_f32_32x32x16_bf16(__builtin_bit_cast(bf16x8, pw[ks]), vf, o[dh], 0, 0, 0);
;         }
;     __builtin_amdgcn_s_setprio(0);
; template <bool MASK>
; __device__ __forceinline__ void sb_weights(f32x16& p0, f32x16& p1, float tlf, int hi, float& R) {
;     ...
;     PS[7] = 1.0f;
; #pragma unroll
;     for (int k = 6; k >= 0; --k) PS[k] = PS[k + 1] * U[k + 1];
; #pragma unroll
;     for (int k = 0; k < 8; ++k) {
;         const float Bk = PS[k] * (hi ? 1.0f : Th[k]) * R;
; #pragma unroll
;         for (int j = 0; j < 4; ++j) { if (k < 4) p0[4 * k + j] *= Bk; else p1[4 * (k - 4) + j] *= Bk; }
;     }
;     R *= PS[0] * U[0];
; }
.LBB0_440:
	v_mul_f32_e32 v180, v222, v223
	v_mul_f32_e32 v181, v78, v180
	v_mul_f32_e32 v182, v79, v181
	v_mul_f32_e32 v183, v76, v182
	v_mul_f32_e32 v78, v77, v183
	v_mul_f32_e32 v64, v69, v78
	v_cndmask_b32_e64 v69, 1.0, v70, s[8:9]
	v_mul_f32_e32 v69, v64, v69
	v_pk_mov_b32 v[76:77], v[6:7], v[8:9] op_sel:[1,0]
	v_mov_b32_e32 v8, v9
	v_mov_b32_e32 v9, v5
	v_cndmask_b32_e64 v5, 1.0, v71, s[8:9]
	v_mul_f32_e32 v70, v179, v69
	v_mul_f32_e32 v5, v78, v5
	v_pk_mul_f32 v[76:77], v[76:77], v[70:71] op_sel_hi:[1,0]
	v_pk_mul_f32 v[8:9], v[8:9], v[70:71] op_sel_hi:[1,0]
	v_mul_f32_e32 v70, v179, v5
	v_cndmask_b32_e64 v5, 1.0, v73, s[8:9]
	v_mov_b32_e32 v78, v48
	v_mov_b32_e32 v79, v14
	v_mul_f32_e32 v5, v183, v5
	v_pk_mul_f32 v[10:11], v[10:11], v[70:71] op_sel_hi:[1,0]
	v_pk_mul_f32 v[70:71], v[78:79], v[70:71] op_sel_hi:[1,0]
	v_mul_f32_e32 v78, v179, v5
	v_cndmask_b32_e64 v5, 1.0, v72, s[8:9]
	v_mov_b32_e32 v14, v13
	v_mul_f32_e32 v5, v182, v5
	v_pk_mov_b32 v[48:49], v[48:49], v[12:13] op_sel:[1,0]
	v_pk_mul_f32 v[12:13], v[14:15], v[78:79] op_sel_hi:[1,0]
	v_mul_f32_e32 v14, v179, v5
	v_cndmask_b32_e64 v5, 1.0, v75, s[8:9]
	v_mov_b32_e32 v72, v56
	v_mov_b32_e32 v73, v54
	v_mul_f32_e32 v5, v181, v5
	v_pk_mul_f32 v[50:51], v[50:51], v[14:15] op_sel_hi:[1,0]
	v_pk_mul_f32 v[14:15], v[72:73], v[14:15] op_sel_hi:[1,0]
	v_mul_f32_e32 v72, v179, v5
	v_cndmask_b32_e64 v5, 1.0, v74, s[8:9]
	v_pk_mov_b32 v[56:57], v[56:57], v[52:53] op_sel:[1,0]
	v_mov_b32_e32 v54, v53
	v_mul_f32_e32 v5, v180, v5
	v_pk_mul_f32 v[56:57], v[56:57], v[72:73] op_sel_hi:[1,0]
	v_pk_mul_f32 v[52:53], v[54:55], v[72:73] op_sel_hi:[1,0]
	v_mul_f32_e32 v54, v179, v5
	v_mov_b32_e32 v72, v66
	v_mov_b32_e32 v73, v62
	v_cndmask_b32_e64 v5, 1.0, v223, s[8:9]
	v_pk_mul_f32 v[58:59], v[58:59], v[54:55] op_sel_hi:[1,0]
	v_pk_mul_f32 v[54:55], v[72:73], v[54:55] op_sel_hi:[1,0]
	v_mul_f32_e32 v72, v179, v5
	v_mov_b32_e32 v62, v61
	v_mov_b32_e32 v69, v0
	v_cndmask_b32_e64 v184, 1.0, v65, s[8:9]
	v_pk_mov_b32 v[66:67], v[66:67], v[60:61] op_sel:[1,0]
	v_pk_mul_f32 v[60:61], v[72:73], v[62:63] op_sel_hi:[0,1]
	v_pk_mul_f32 v[62:63], v[68:69], v[64:65]
	v_mov_b32_e32 v7, v4
	v_mul_f32_e32 v0, v62, v184
	v_mul_f32_e32 v0, v179, v0
	v_pk_mul_f32 v[2:3], v[2:3], v[0:1] op_sel_hi:[1,0]
	v_pk_mul_f32 v[4:5], v[6:7], v[0:1] op_sel_hi:[1,0]
	v_mul_f32_e32 v0, v62, v63
	v_pk_mul_f32 v[48:49], v[48:49], v[78:79] op_sel_hi:[1,0]
	v_pk_mul_f32 v[66:67], v[72:73], v[66:67] op_sel_hi:[0,1]
	v_mul_f32_e32 v179, v179, v0
	v_cvt_pk_bf16_f32 v2, v2, v3
	v_cvt_pk_bf16_f32 v3, v4, v5
	v_cvt_pk_bf16_f32 v4, v76, v77
	v_cvt_pk_bf16_f32 v5, v8, v9
	v_cvt_pk_bf16_f32 v6, v10, v11
	v_cvt_pk_bf16_f32 v7, v70, v71
	v_cvt_pk_bf16_f32 v8, v48, v49
	v_cvt_pk_bf16_f32 v9, v12, v13
	v_cvt_pk_bf16_f32 v10, v50, v51
	v_cvt_pk_bf16_f32 v11, v14, v15
	v_cvt_pk_bf16_f32 v12, v56, v57
	v_cvt_pk_bf16_f32 v13, v52, v53
	v_cvt_pk_bf16_f32 v48, v58, v59
	v_cvt_pk_bf16_f32 v49, v54, v55
	v_cvt_pk_bf16_f32 v50, v66, v67
	v_cvt_pk_bf16_f32 v51, v60, v61
	s_setprio 1
	v_add_u32_e32 v0, s50, v177
	ds_read_b64_tr_b16 v[52:53], v0 offset:23552
	ds_read_b64_tr_b16 v[54:55], v0 offset:24064
	s_waitcnt lgkmcnt(2)
	v_mfma_f32_32x32x16_bf16 v[16:31], v[2:5], v[224:227], v[16:31]
	v_mfma_f32_32x32x16_bf16 v[16:31], v[6:9], v[228:231], v[16:31]
	v_mfma_f32_32x32x16_bf16 v[16:31], v[10:13], v[232:235], v[16:31]
	v_mfma_f32_32x32x16_bf16 v[16:31], v[48:51], v[236:239], v[16:31]
	v_mfma_f32_32x32x16_bf16 v[32:47], v[2:5], v[240:243], v[32:47]
	v_mfma_f32_32x32x16_bf16 v[32:47], v[6:9], v[244:247], v[32:47]
	v_mfma_f32_32x32x16_bf16 v[32:47], v[10:13], v[248:251], v[32:47]
	s_waitcnt lgkmcnt(0)
	v_mfma_f32_32x32x16_bf16 v[32:47], v[48:51], v[52:55], v[32:47]
	s_setprio 0
	v_cmp_eq_f32_e32 vcc, 0, v179
	s_cmp_eq_u64 vcc, exec
	s_cselect_b64 s[68:69], -1, 0
	s_add_i32 s50, s83, 1
	s_cmp_ge_u32 s50, s81
	s_cbranch_scc0 .LBB0_444

; #define LAS __attribute__((address_space(3)))
; template <int VAR>
; __device__ __forceinline__ void attn_unit(LAS unsigned char* lds, const AttnArgs& A, int b, int h, int qb, const int tid) {
;     ...
;                 f32x16 p0, p1;
; #pragma unroll
;                 for (int r = 0; r < 16; ++r) { p0[r] = 0.f; p1[r] = 0.f; }
;                 __builtin_amdgcn_s_setprio(1);
; #pragma unroll
;                 for (int d0 = 0; d0 < 4; ++d0) {
;                     const bf16x8 b0 = *(const LAS bf16x8*)(kb + d0 * 2048), b1 = *(const LAS bf16x8*)(kb + d0 * 2048 + 512);
;                     p0 = __builtin_amdgcn_mfma_f32_32x32x16_bf16(b0, qr[d0], p0, 0, 0, 0);
;                     p1 = __builtin_amdgcn_mfma_f32_32x32x16_bf16(b1, qr[d0], p1, 0, 0, 0);
;                 }
;                 __builtin_amdgcn_s_setprio(0);
;                 if (VAR == 0) {
;                     const LAS float* fs = FS + buf * 64 + 4 * hi;
; #pragma unroll
;                     for (int a = 0; a < 4; ++a) {
;                         const f32x4 f0 = *(const LAS f32x4*)(fs + 8 * a), f1 = *(const LAS f32x4*)(fs + 32 + 8 * a);
; #pragma unroll
;                         for (int j = 0; j < 4; ++j) { p0[4 * a + j] += Ft - f0[j]; p1[4 * a + j] += Ft - f1[j]; }
;                     }
;                     if (diag) {
;                         const float tlf = (float)tl;
; #pragma unroll
;                         for (int r = 0; r < 16; ++r) { const float c0 = (float)((r & 3) + 8 * (r >> 2));
;                             p0[r] = __builtin_fmaf(fminf(tlf - c0, 0.f), 1e30f, p0[r]); p1[r] = __builtin_fmaf(fminf(tlf - (c0 + 32.0f), 0.f), 1e30f, p1[r]); }
;                     }
.LBB0_519:
	s_add_i32 s38, s68, 2
	s_and_b32 s82, s69, 1
	s_cmp_gt_i32 s38, s79
	s_cselect_b64 s[38:39], -1, 0
	s_or_b64 s[38:39], s[38:39], s[70:71]
	s_and_b64 vcc, exec, s[38:39]
	s_cbranch_vccnz .LBB0_528
	s_lshl_b32 s51, s82, 13
	s_lshl_b32 s38, s82, 8
	v_add_u32_e32 v136, s51, v141
	s_add_i32 s50, s38, 0
	s_cmp_lg_u32 s81, s69
	s_setprio 1
	ds_read_b128 v[206:209], v136
	ds_read_b128 v[210:213], v136 offset:2048
	ds_read_b128 v[214:217], v136 offset:512
	ds_read_b128 v[218:221], v136 offset:2560
	ds_read_b128 v[222:225], v136 offset:4096
	ds_read_b128 v[226:229], v136 offset:4608
	ds_read_b128 v[230:233], v136 offset:6144
	ds_read_b128 v[234:237], v136 offset:6656
	v_lshl_add_u32 v147, v142, 2, s50
	ds_read_b128 v[238:241], v147 offset:32768
	ds_read_b128 v[242:245], v147 offset:32800
	ds_read_b128 v[246:249], v147 offset:32896
	ds_read_b128 v[250:253], v147 offset:32928
	ds_read_b128 v[178:181], v147 offset:32832
	ds_read_b128 v[182:185], v147 offset:32960
	ds_read_b128 v[186:189], v147 offset:32864
	ds_read_b128 v[190:193], v147 offset:32992
	s_waitcnt lgkmcnt(15)
	v_mfma_f32_32x32x16_bf16 v[34:49], v[206:209], v[66:69], 0
	s_waitcnt lgkmcnt(14)
	v_mfma_f32_32x32x16_bf16 v[34:49], v[210:213], v[70:73], v[34:49]
	s_waitcnt lgkmcnt(13)
	v_mfma_f32_32x32x16_bf16 v[50:65], v[214:217], v[66:69], 0
	s_waitcnt lgkmcnt(12)
	v_mfma_f32_32x32x16_bf16 v[50:65], v[218:221], v[70:73], v[50:65]
	s_waitcnt lgkmcnt(11)
	v_mfma_f32_32x32x16_bf16 v[34:49], v[222:225], v[74:77], v[34:49]
	s_waitcnt lgkmcnt(10)
	v_mfma_f32_32x32x16_bf16 v[50:65], v[226:229], v[74:77], v[50:65]
	s_waitcnt lgkmcnt(9)
	v_mfma_f32_32x32x16_bf16 v[34:49], v[230:233], v[78:81], v[34:49]
	s_waitcnt lgkmcnt(8)
	v_mfma_f32_32x32x16_bf16 v[50:65], v[234:237], v[78:81], v[50:65]
	s_setprio 0
	s_nop 7
	s_waitcnt lgkmcnt(7)
	v_pk_add_f32 v[136:137], v[98:99], v[238:239] neg_lo:[0,1] neg_hi:[0,1]
	s_nop 1
	v_pk_add_f32 v[136:137], v[34:35], v[136:137]
	s_waitcnt lgkmcnt(5)
	v_pk_add_f32 v[34:35], v[98:99], v[246:247] neg_lo:[0,1] neg_hi:[0,1]
	s_nop 0
	v_pk_add_f32 v[50:51], v[50:51], v[34:35]
	v_pk_add_f32 v[34:35], v[98:99], v[240:241] neg_lo:[0,1] neg_hi:[0,1]
	v_pk_add_f32 v[34:35], v[36:37], v[34:35]
	v_pk_add_f32 v[36:37], v[98:99], v[248:249] neg_lo:[0,1] neg_hi:[0,1]
	s_nop 0
	v_pk_add_f32 v[36:37], v[52:53], v[36:37]
	v_pk_add_f32 v[52:53], v[98:99], v[242:243] neg_lo:[0,1] neg_hi:[0,1]
	s_nop 0
	v_pk_add_f32 v[52:53], v[38:39], v[52:53]
	s_waitcnt lgkmcnt(4)
	v_pk_add_f32 v[38:39], v[98:99], v[250:251] neg_lo:[0,1] neg_hi:[0,1]
	s_nop 0
	v_pk_add_f32 v[54:55], v[54:55], v[38:39]
	v_pk_add_f32 v[38:39], v[98:99], v[244:245] neg_lo:[0,1] neg_hi:[0,1]
	s_nop 0
	v_pk_add_f32 v[38:39], v[40:41], v[38:39]
	v_pk_add_f32 v[40:41], v[98:99], v[252:253] neg_lo:[0,1] neg_hi:[0,1]
	v_pk_add_f32 v[40:41], v[56:57], v[40:41]
	s_waitcnt lgkmcnt(3)
	v_pk_add_f32 v[56:57], v[98:99], v[178:179] neg_lo:[0,1] neg_hi:[0,1]
	s_nop 0
	v_pk_add_f32 v[56:57], v[42:43], v[56:57]
	s_waitcnt lgkmcnt(2)
	v_pk_add_f32 v[42:43], v[98:99], v[182:183] neg_lo:[0,1] neg_hi:[0,1]
	s_nop 0
	v_pk_add_f32 v[58:59], v[58:59], v[42:43]
	v_pk_add_f32 v[42:43], v[98:99], v[180:181] neg_lo:[0,1] neg_hi:[0,1]
	s_nop 0
	v_pk_add_f32 v[42:43], v[44:45], v[42:43]
	v_pk_add_f32 v[44:45], v[98:99], v[184:185] neg_lo:[0,1] neg_hi:[0,1]
	v_pk_add_f32 v[44:45], v[60:61], v[44:45]
	s_waitcnt lgkmcnt(1)
	v_pk_add_f32 v[60:61], v[98:99], v[186:187] neg_lo:[0,1] neg_hi:[0,1]
	s_nop 0
	v_pk_add_f32 v[60:61], v[46:47], v[60:61]
	s_waitcnt lgkmcnt(0)
	v_pk_add_f32 v[46:47], v[98:99], v[190:191] neg_lo:[0,1] neg_hi:[0,1]
	s_nop 0
	v_pk_add_f32 v[62:63], v[62:63], v[46:47]
	v_pk_add_f32 v[46:47], v[98:99], v[188:189] neg_lo:[0,1] neg_hi:[0,1]
	s_nop 0
	v_pk_add_f32 v[46:47], v[48:49], v[46:47]
	v_pk_add_f32 v[48:49], v[98:99], v[192:193] neg_lo:[0,1] neg_hi:[0,1]
	s_nop 0
	v_pk_add_f32 v[48:49], v[64:65], v[48:49]
	v_add_u32_e32 v194, s51, v143
	ds_read_b64_tr_b16 v[206:207], v194 offset:16384
	ds_read_b64_tr_b16 v[208:209], v194 offset:16896
	ds_read_b64_tr_b16 v[210:211], v194 offset:17408
	ds_read_b64_tr_b16 v[212:213], v194 offset:17920
	ds_read_b64_tr_b16 v[214:215], v194 offset:18432
	ds_read_b64_tr_b16 v[216:217], v194 offset:18944
	ds_read_b64_tr_b16 v[218:219], v194 offset:19456
	ds_read_b64_tr_b16 v[220:221], v194 offset:19968
	ds_read_b64_tr_b16 v[222:223], v194 offset:20480
	ds_read_b64_tr_b16 v[224:225], v194 offset:20992
	ds_read_b64_tr_b16 v[226:227], v194 offset:21504
	ds_read_b64_tr_b16 v[228:229], v194 offset:22016
	ds_read_b64_tr_b16 v[230:231], v194 offset:22528
	ds_read_b64_tr_b16 v[232:233], v194 offset:23040
	ds_read_b64_tr_b16 v[234:235], v194 offset:23552
	ds_read_b64_tr_b16 v[236:237], v194 offset:24064
	s_cbranch_scc1 .LBB0_522
	v_pk_fma_f32 v[46:47], v[132:133], s[62:63], v[46:47] op_sel_hi:[1,0,1]
	v_pk_fma_f32 v[60:61], v[128:129], s[62:63], v[60:61] op_sel_hi:[1,0,1]
	v_pk_fma_f32 v[42:43], v[120:121], s[62:63], v[42:43] op_sel_hi:[1,0,1]
	v_pk_fma_f32 v[56:57], v[116:117], s[62:63], v[56:57] op_sel_hi:[1,0,1]
	v_pk_fma_f32 v[38:39], v[112:113], s[62:63], v[38:39] op_sel_hi:[1,0,1]
	v_pk_fma_f32 v[52:53], v[108:109], s[62:63], v[52:53] op_sel_hi:[1,0,1]
	v_pk_fma_f32 v[34:35], v[104:105], s[62:63], v[34:35] op_sel_hi:[1,0,1]
	v_pk_fma_f32 v[136:137], v[100:101], s[62:63], v[136:137] op_sel_hi:[1,0,1]
	v_pk_fma_f32 v[48:49], v[134:135], s[62:63], v[48:49] op_sel_hi:[1,0,1]
	v_pk_fma_f32 v[62:63], v[130:131], s[62:63], v[62:63] op_sel_hi:[1,0,1]
	v_pk_fma_f32 v[44:45], v[126:127], s[62:63], v[44:45] op_sel_hi:[1,0,1]
	v_pk_fma_f32 v[58:59], v[118:119], s[62:63], v[58:59] op_sel_hi:[1,0,1]
	v_pk_fma_f32 v[40:41], v[114:115], s[62:63], v[40:41] op_sel_hi:[1,0,1]
	v_pk_fma_f32 v[54:55], v[110:111], s[62:63], v[54:55] op_sel_hi:[1,0,1]
	v_pk_fma_f32 v[36:37], v[106:107], s[62:63], v[36:37] op_sel_hi:[1,0,1]
	v_pk_fma_f32 v[50:51], v[102:103], s[62:63], v[50:51] op_sel_hi:[1,0,1]
; #define LAS __attribute__((address_space(3)))
; __device__ __forceinline__ unsigned cvtpk(float lo, float hi) { f32x2_t v = {lo, hi}; bf16x2_t b = __builtin_convertvector(v, bf16x2_t); return __builtin_bit_cast(unsigned, b); }
; __device__ __forceinline__ float pair_max(float v) { float a, b; lohi(v, a, b); return fmaxf(a, b); }
; __device__ __forceinline__ void pv(f32x16 (&o)[2], const LAS unsigned char* vp, const f32x16& p0, const f32x16& p1) {
;     u32x4 pw[4];
;     pw[0] = (u32x4){cvtpk(p0[0], p0[1]), cvtpk(p0[2], p0[3]), cvtpk(p0[4], p0[5]), cvtpk(p0[6], p0[7])};
;     pw[1] = (u32x4){cvtpk(p0[8], p0[9]), cvtpk(p0[10], p0[11]), cvtpk(p0[12], p0[13]), cvtpk(p0[14], p0[15])};
;     pw[2] = (u32x4){cvtpk(p1[0], p1[1]), cvtpk(p1[2], p1[3]), cvtpk(p1[4], p1[5]), cvtpk(p1[6], p1[7])};
;     pw[3] = (u32x4){cvtpk(p1[8], p1[9]), cvtpk(p1[10], p1[11]), cvtpk(p1[12], p1[13]), cvtpk(p1[14], p1[15])};
;     __builtin_amdgcn_s_setprio(1);
; #pragma unroll
;     for (int dh = 0; dh < 2; ++dh)
; #pragma unroll
;         for (int ks = 0; ks < 4; ++ks) {
;             const s16x4 lo = vtr(vp + dh * 4096 + ks * 1024), hi_ = vtr(vp + dh * 4096 + ks * 1024 + 512);
;             const bf16x8 vf = __builtin_shufflevector(lo, hi_, 0, 1, 2, 3, 4, 5, 6, 7);
;             o[dh] = __builtin_amdgcn_mfma_f32_32x32x16_bf16(__builtin_bit_cast(bf16x8, pw[ks]), vf, o[dh], 0, 0, 0);
;         }
;     __builtin_amdgcn_s_setprio(0);
; __device__ __forceinline__ void softmax_pv(f32x16& p0, f32x16& p1, float& m, float& l, f32x16 (&o)[2], LAS float* wsf, const LAS unsigned char* vp, int r32, int hi) {
;     float rm = fmaxf(p0[0], p1[0]);
; #pragma unroll
;     for (int r = 1; r < 16; ++r) rm = fmaxf(rm, fmaxf(p0[r], p1[r]));
;     rm = pair_max(rm);
;     if (__all(rm - m < -151.0f)) return;
;     const float mnew = fmaxf(m, rm), alpha = __builtin_amdgcn_exp2f(m - mnew);
;     m = mnew;
;     float s = 0.f;
; #pragma unroll
;     for (int r = 0; r < 16; ++r) { p0[r] = __builtin_amdgcn_exp2f(p0[r] - mnew); p1[r] = __builtin_amdgcn_exp2f(p1[r] - mnew); s += p0[r] + p1[r]; }
;     l = l * alpha + s;
;     if (__any(alpha != 1.0f)) {
;         if (hi == 0) wsf[r32] = alpha;
; #pragma unroll
;         for (int r = 0; r < 16; ++r) { const float f = wsf[(r & 3) + 8 * (r >> 2) + 4 * hi]; o[0][r] *= f; o[1][r] *= f; }
;     }
;     pv(o, vp, p0, p1);
.LBB0_522:
	s_nop 0
	v_max3_f32 v64, v51, v137, v36
	v_max3_f32 v65, v34, v37, v35
	v_max3_f32 v64, v64, v54, v52
	v_max3_f32 v65, v65, v55, v53
	v_max3_f32 v64, v64, v40, v38
	v_max3_f32 v65, v65, v41, v39
	v_max3_f32 v64, v64, v58, v56
	v_max3_f32 v65, v65, v59, v57
	v_max3_f32 v64, v64, v44, v42
	v_max3_f32 v65, v65, v45, v43
	v_max3_f32 v64, v64, v62, v60
	v_max3_f32 v65, v65, v63, v61
	v_max3_f32 v64, v64, v48, v46
	v_max3_f32 v65, v65, v49, v47
	v_max3_f32 v64, v64, v136, v50
	v_max_f32_e32 v64, v64, v65
	v_mov_b32_e32 v65, v64
	s_nop 1
	v_permlane32_swap_b32_e32 v64, v65
	v_max_f32_e32 v65, v65, v65
	v_max_f32_e32 v64, v64, v64
	v_max_f32_e32 v64, v64, v65
	v_sub_f32_e32 v65, v64, v146
	v_cmp_gt_f32_e32 vcc, s36, v65
	s_cmp_eq_u64 vcc, exec
	s_cbranch_scc1 .LBB0_533
	v_max_f32_e32 v64, v64, v64
	v_add_f32_e32 v65, 0x41000000, v146
	v_cmp_gt_f32_e32 vcc, v64, v65
	s_nop 1
	v_cndmask_b32_e32 v64, v146, v64, vcc
	v_sub_f32_e32 v65, v146, v64
	v_exp_f32_e32 v65, v65
	s_nop 0
	v_cmp_neq_f32_e32 vcc, 1.0, v65
	s_cbranch_vccz .LBB0_527
	s_and_saveexec_b64 s[70:71], s[10:11]
	ds_write_b32 v144, v65 offset:36864
	s_or_b64 exec, exec, s[70:71]
	ds_read_b128 v[146:149], v0 offset:36960
	ds_read_b128 v[150:153], v0 offset:36928
	ds_read_b128 v[166:169], v0 offset:36896
	ds_read_b128 v[170:173], v0 offset:36864
	s_waitcnt lgkmcnt(3)
	v_pk_mul_f32 v[30:31], v[30:31], v[146:147]
	s_waitcnt lgkmcnt(2)
	v_pk_mul_f32 v[26:27], v[26:27], v[150:151]
	s_waitcnt lgkmcnt(1)
	v_pk_mul_f32 v[22:23], v[22:23], v[166:167]
	v_pk_mul_f32 v[32:33], v[32:33], v[148:149]
	v_pk_mul_f32 v[28:29], v[28:29], v[152:153]
	v_pk_mul_f32 v[24:25], v[24:25], v[168:169]
	s_waitcnt lgkmcnt(0)
	v_pk_mul_f32 v[20:21], v[20:21], v[172:173]
	v_pk_mul_f32 v[18:19], v[18:19], v[170:171]
	v_pk_mul_f32 v[14:15], v[14:15], v[146:147]
	v_pk_mul_f32 v[10:11], v[10:11], v[150:151]
	v_pk_mul_f32 v[6:7], v[6:7], v[166:167]
	v_pk_mul_f32 v[16:17], v[16:17], v[148:149]
	v_pk_mul_f32 v[12:13], v[12:13], v[152:153]
	v_pk_mul_f32 v[8:9], v[8:9], v[168:169]
	v_pk_mul_f32 v[4:5], v[4:5], v[172:173]
	v_pk_mul_f32 v[2:3], v[2:3], v[170:171]
.LBB0_527:
	v_sub_f32_e32 v136, v136, v64
	v_sub_f32_e32 v50, v50, v64
	v_sub_f32_e32 v34, v34, v64
	v_exp_f32_e32 v136, v136
	v_exp_f32_e32 v50, v50
	v_sub_f32_e32 v137, v137, v64
	v_sub_f32_e32 v51, v51, v64
	v_exp_f32_e32 v148, v34
	v_sub_f32_e32 v34, v36, v64
	v_exp_f32_e32 v137, v137
	v_exp_f32_e32 v51, v51
	v_exp_f32_e32 v149, v34
	v_sub_f32_e32 v34, v35, v64
	v_exp_f32_e32 v35, v34
	v_sub_f32_e32 v34, v37, v64
	v_exp_f32_e32 v150, v34
	v_sub_f32_e32 v37, v52, v64
	v_sub_f32_e32 v52, v54, v64
	v_add_f32_e32 v146, v136, v50
	v_exp_f32_e32 v37, v37
	v_exp_f32_e32 v52, v52
	v_sub_f32_e32 v53, v53, v64
	v_sub_f32_e32 v54, v55, v64
	v_add_f32_e32 v146, 0, v146
	v_add_f32_e32 v147, v137, v51
	v_exp_f32_e32 v53, v53
	v_exp_f32_e32 v54, v54
	v_sub_f32_e32 v38, v38, v64
	v_sub_f32_e32 v40, v40, v64
	v_add_f32_e32 v34, v147, v146
	v_add_f32_e32 v36, v148, v149
	v_exp_f32_e32 v38, v38
	v_exp_f32_e32 v55, v40
	v_sub_f32_e32 v39, v39, v64
	v_sub_f32_e32 v40, v41, v64
	v_add_f32_e32 v34, v36, v34
	v_add_f32_e32 v36, v35, v150
	v_exp_f32_e32 v39, v39
	v_exp_f32_e32 v146, v40
	v_sub_f32_e32 v40, v56, v64
	v_sub_f32_e32 v41, v58, v64
	v_add_f32_e32 v34, v36, v34
	v_add_f32_e32 v36, v37, v52
	v_exp_f32_e32 v40, v40
	v_exp_f32_e32 v56, v41
	v_sub_f32_e32 v41, v57, v64
	v_sub_f32_e32 v57, v59, v64
	v_add_f32_e32 v34, v36, v34
	v_add_f32_e32 v36, v53, v54
	v_exp_f32_e32 v41, v41
	v_exp_f32_e32 v57, v57
	v_sub_f32_e32 v42, v42, v64
	v_sub_f32_e32 v44, v44, v64
	v_add_f32_e32 v34, v36, v34
	v_add_f32_e32 v36, v38, v55
	v_exp_f32_e32 v42, v42
	v_exp_f32_e32 v58, v44
	v_sub_f32_e32 v43, v43, v64
	v_sub_f32_e32 v44, v45, v64
	v_add_f32_e32 v34, v36, v34
	v_add_f32_e32 v36, v39, v146
	v_exp_f32_e32 v43, v43
	v_exp_f32_e32 v59, v44
	v_sub_f32_e32 v44, v60, v64
	v_sub_f32_e32 v45, v62, v64
	v_add_f32_e32 v34, v36, v34
	v_add_f32_e32 v36, v40, v56
	v_exp_f32_e32 v44, v44
	v_exp_f32_e32 v60, v45
	v_sub_f32_e32 v45, v61, v64
	v_sub_f32_e32 v61, v63, v64
	v_add_f32_e32 v34, v36, v34
	v_add_f32_e32 v36, v41, v57
	v_exp_f32_e32 v45, v45
	v_exp_f32_e32 v61, v61
	v_sub_f32_e32 v46, v46, v64
	v_sub_f32_e32 v48, v48, v64
	v_add_f32_e32 v34, v36, v34
	v_add_f32_e32 v36, v42, v58
	v_exp_f32_e32 v46, v46
	v_exp_f32_e32 v62, v48
	v_sub_f32_e32 v47, v47, v64
	v_sub_f32_e32 v48, v49, v64
	v_add_f32_e32 v34, v36, v34
	v_add_f32_e32 v36, v43, v59
	v_exp_f32_e32 v47, v47
	v_exp_f32_e32 v49, v48
	v_add_f32_e32 v34, v36, v34
	v_add_f32_e32 v36, v44, v60
	v_add_f32_e32 v34, v36, v34
	v_add_f32_e32 v36, v45, v61
	v_add_f32_e32 v34, v36, v34
	v_add_f32_e32 v36, v46, v62
	v_add_f32_e32 v34, v36, v34
	v_add_f32_e32 v36, v47, v49
	v_add_f32_e32 v63, v36, v34
	v_fmac_f32_e32 v63, v145, v65
	v_cvt_pk_bf16_f32 v34, v136, v137
	v_cvt_pk_bf16_f32 v35, v148, v35
	v_cvt_pk_bf16_f32 v36, v37, v53
	v_cvt_pk_bf16_f32 v37, v38, v39
	v_cvt_pk_bf16_f32 v38, v40, v41
	v_cvt_pk_bf16_f32 v39, v42, v43
	v_cvt_pk_bf16_f32 v40, v44, v45
	v_cvt_pk_bf16_f32 v41, v46, v47
	v_cvt_pk_bf16_f32 v42, v50, v51
	v_cvt_pk_bf16_f32 v43, v149, v150
	v_cvt_pk_bf16_f32 v44, v52, v54
	v_cvt_pk_bf16_f32 v45, v55, v146
	v_cvt_pk_bf16_f32 v46, v56, v57
	v_cvt_pk_bf16_f32 v47, v58, v59
	v_cvt_pk_bf16_f32 v48, v60, v61
	v_cvt_pk_bf16_f32 v49, v62, v49
	s_setprio 1
	s_waitcnt lgkmcnt(0)
	v_mfma_f32_32x32x16_bf16 v[18:33], v[34:37], v[206:209], v[18:33]
	v_mfma_f32_32x32x16_bf16 v[18:33], v[38:41], v[210:213], v[18:33]
	v_mfma_f32_32x32x16_bf16 v[18:33], v[42:45], v[214:217], v[18:33]
	v_mfma_f32_32x32x16_bf16 v[18:33], v[46:49], v[218:221], v[18:33]
	v_mfma_f32_32x32x16_bf16 v[2:17], v[34:37], v[222:225], v[2:17]
	v_mfma_f32_32x32x16_bf16 v[2:17], v[38:41], v[226:229], v[2:17]
	v_mfma_f32_32x32x16_bf16 v[2:17], v[42:45], v[230:233], v[2:17]
	v_mfma_f32_32x32x16_bf16 v[2:17], v[46:49], v[234:237], v[2:17]
	s_setprio 0
	v_mov_b32_e32 v145, v63
	s_branch .LBB0_534
